# f32 mode-0 epilogue full-line stores, reworked to use only s100/s101 as scalar temporaries
# speedup vs baseline: 1.0038x; 1.0038x over previous
; __device__ __forceinline__ void epilogue(const f32x4 (&acc)[2][2][4][2], const Unit& u, LAS unsigned char* lds, int wr, int wc, int fr, int fq) {
;     ...
;     if (mode == 0 || mode >= 5) {
;         float* C = (float*)Cp; const float* bias = (const float*)rfl_ptr(jobs[u.j].bias);
; #pragma unroll
;         for (int ai = 0; ai < 2; ++ai)
; #pragma unroll
;             for (int m = 0; m < 4; ++m) { float* rowp = C + (size_t)(row0 + ai * HALF + m * 16) * ldc + col0;
; #pragma unroll
;                 for (int bj = 0; bj < 2; ++bj)
; #pragma unroll
;                     for (int n = 0; n < 2; ++n) { f32x4 v = acc[ai][bj][m][n];
;                         if (mode >= 5) { v += *(const f32x4*)(bias + col0 + bj * HALF + n * 16);
; #pragma unroll
;                             for (int q = 0; q < 4; ++q) { const float sg = __builtin_amdgcn_rcpf(1.f + __expf(-v[q])); v[q] = mode == 5 ? __expf(-0.6065306597126334f * sg) : sg; } }
;                         *(f32x4*)(rowp + bj * HALF + n * 16) = v; }
;                 asm volatile("" ::: "memory"); }
.Lepi_f0:
	s_lshl_b64 s[100:101], s[26:27], 5
	s_lshl_b64 s[2:3], s[26:27], 6
	v_mov_b32_e32 v250, s100
	v_mov_b32_e32 v251, s101
	v_sub_co_u32_e32 v250, vcc, 64, v250
	s_nop 1
	v_subb_co_u32_e32 v251, vcc, 0, v251, vcc
	v_mbcnt_lo_u32_b32 v248, -1, 0
	v_mbcnt_hi_u32_b32 v248, -1, v248
	v_and_b32_e32 v248, 8, v248
	v_cmp_ne_u32_e32 vcc, 0, v248
	s_nop 1
	v_cndmask_b32_e32 v250, 0, v250, vcc
	v_cndmask_b32_e32 v251, 0, v251, vcc
	v_lshl_add_u64 v[144:145], v[144:145], 0, v[250:251]
	v_lshl_add_u64 v[142:143], v[144:145], 0, s[100:101]
	v_mov_b32_dpp v240, v124 row_ror:8 row_mask:0xf bank_mask:0xf
	v_mov_b32_dpp v241, v125 row_ror:8 row_mask:0xf bank_mask:0xf
	v_mov_b32_dpp v242, v126 row_ror:8 row_mask:0xf bank_mask:0xf
	v_mov_b32_dpp v243, v127 row_ror:8 row_mask:0xf bank_mask:0xf
	v_mov_b32_dpp v124, v128 row_ror:8 row_mask:0xf bank_mask:0x3
	v_mov_b32_dpp v125, v129 row_ror:8 row_mask:0xf bank_mask:0x3
	v_mov_b32_dpp v126, v130 row_ror:8 row_mask:0xf bank_mask:0x3
	v_mov_b32_dpp v127, v131 row_ror:8 row_mask:0xf bank_mask:0x3
	v_mov_b32_dpp v128, v240 quad_perm:[0,1,2,3] row_mask:0xf bank_mask:0xc
	v_mov_b32_dpp v129, v241 quad_perm:[0,1,2,3] row_mask:0xf bank_mask:0xc
	v_mov_b32_dpp v130, v242 quad_perm:[0,1,2,3] row_mask:0xf bank_mask:0xc
	v_mov_b32_dpp v131, v243 quad_perm:[0,1,2,3] row_mask:0xf bank_mask:0xc
	global_store_dwordx4 v[144:145], v[128:131], off
	global_store_dwordx4 v[142:143], v[124:127], off
	v_mov_b32_dpp v240, v116 row_ror:8 row_mask:0xf bank_mask:0xf
	v_mov_b32_dpp v241, v117 row_ror:8 row_mask:0xf bank_mask:0xf
	v_mov_b32_dpp v242, v118 row_ror:8 row_mask:0xf bank_mask:0xf
	v_mov_b32_dpp v243, v119 row_ror:8 row_mask:0xf bank_mask:0xf
	v_mov_b32_dpp v116, v120 row_ror:8 row_mask:0xf bank_mask:0x3
	v_mov_b32_dpp v117, v121 row_ror:8 row_mask:0xf bank_mask:0x3
	v_mov_b32_dpp v118, v122 row_ror:8 row_mask:0xf bank_mask:0x3
	v_mov_b32_dpp v119, v123 row_ror:8 row_mask:0xf bank_mask:0x3
	v_mov_b32_dpp v120, v240 quad_perm:[0,1,2,3] row_mask:0xf bank_mask:0xc
	v_mov_b32_dpp v121, v241 quad_perm:[0,1,2,3] row_mask:0xf bank_mask:0xc
	v_mov_b32_dpp v122, v242 quad_perm:[0,1,2,3] row_mask:0xf bank_mask:0xc
	v_mov_b32_dpp v123, v243 quad_perm:[0,1,2,3] row_mask:0xf bank_mask:0xc
	global_store_dwordx4 v[144:145], v[120:123], off offset:512
	global_store_dwordx4 v[142:143], v[116:119], off offset:512
	v_lshl_add_u64 v[144:145], s[2:3], 0, v[144:145]
	v_lshl_add_u64 v[142:143], s[2:3], 0, v[142:143]
	v_mov_b32_dpp v240, v108 row_ror:8 row_mask:0xf bank_mask:0xf
	v_mov_b32_dpp v241, v109 row_ror:8 row_mask:0xf bank_mask:0xf
	v_mov_b32_dpp v242, v110 row_ror:8 row_mask:0xf bank_mask:0xf
	v_mov_b32_dpp v243, v111 row_ror:8 row_mask:0xf bank_mask:0xf
	v_mov_b32_dpp v108, v112 row_ror:8 row_mask:0xf bank_mask:0x3
	v_mov_b32_dpp v109, v113 row_ror:8 row_mask:0xf bank_mask:0x3
	v_mov_b32_dpp v110, v114 row_ror:8 row_mask:0xf bank_mask:0x3
	v_mov_b32_dpp v111, v115 row_ror:8 row_mask:0xf bank_mask:0x3
	v_mov_b32_dpp v112, v240 quad_perm:[0,1,2,3] row_mask:0xf bank_mask:0xc
	v_mov_b32_dpp v113, v241 quad_perm:[0,1,2,3] row_mask:0xf bank_mask:0xc
	v_mov_b32_dpp v114, v242 quad_perm:[0,1,2,3] row_mask:0xf bank_mask:0xc
	v_mov_b32_dpp v115, v243 quad_perm:[0,1,2,3] row_mask:0xf bank_mask:0xc
	global_store_dwordx4 v[144:145], v[112:115], off
	global_store_dwordx4 v[142:143], v[108:111], off
	v_mov_b32_dpp v240, v100 row_ror:8 row_mask:0xf bank_mask:0xf
	v_mov_b32_dpp v241, v101 row_ror:8 row_mask:0xf bank_mask:0xf
	v_mov_b32_dpp v242, v102 row_ror:8 row_mask:0xf bank_mask:0xf
	v_mov_b32_dpp v243, v103 row_ror:8 row_mask:0xf bank_mask:0xf
	v_mov_b32_dpp v100, v104 row_ror:8 row_mask:0xf bank_mask:0x3
	v_mov_b32_dpp v101, v105 row_ror:8 row_mask:0xf bank_mask:0x3
	v_mov_b32_dpp v102, v106 row_ror:8 row_mask:0xf bank_mask:0x3
	v_mov_b32_dpp v103, v107 row_ror:8 row_mask:0xf bank_mask:0x3
	v_mov_b32_dpp v104, v240 quad_perm:[0,1,2,3] row_mask:0xf bank_mask:0xc
	v_mov_b32_dpp v105, v241 quad_perm:[0,1,2,3] row_mask:0xf bank_mask:0xc
	v_mov_b32_dpp v106, v242 quad_perm:[0,1,2,3] row_mask:0xf bank_mask:0xc
	v_mov_b32_dpp v107, v243 quad_perm:[0,1,2,3] row_mask:0xf bank_mask:0xc
	global_store_dwordx4 v[144:145], v[104:107], off offset:512
	global_store_dwordx4 v[142:143], v[100:103], off offset:512
	v_lshl_add_u64 v[144:145], s[2:3], 0, v[144:145]
	v_lshl_add_u64 v[142:143], s[2:3], 0, v[142:143]
	v_mov_b32_dpp v240, v92 row_ror:8 row_mask:0xf bank_mask:0xf
	v_mov_b32_dpp v241, v93 row_ror:8 row_mask:0xf bank_mask:0xf
	v_mov_b32_dpp v242, v94 row_ror:8 row_mask:0xf bank_mask:0xf
	v_mov_b32_dpp v243, v95 row_ror:8 row_mask:0xf bank_mask:0xf
	v_mov_b32_dpp v92, v96 row_ror:8 row_mask:0xf bank_mask:0x3
	v_mov_b32_dpp v93, v97 row_ror:8 row_mask:0xf bank_mask:0x3
	v_mov_b32_dpp v94, v98 row_ror:8 row_mask:0xf bank_mask:0x3
	v_mov_b32_dpp v95, v99 row_ror:8 row_mask:0xf bank_mask:0x3
	v_mov_b32_dpp v96, v240 quad_perm:[0,1,2,3] row_mask:0xf bank_mask:0xc
	v_mov_b32_dpp v97, v241 quad_perm:[0,1,2,3] row_mask:0xf bank_mask:0xc
	v_mov_b32_dpp v98, v242 quad_perm:[0,1,2,3] row_mask:0xf bank_mask:0xc
	v_mov_b32_dpp v99, v243 quad_perm:[0,1,2,3] row_mask:0xf bank_mask:0xc
	global_store_dwordx4 v[144:145], v[96:99], off
	global_store_dwordx4 v[142:143], v[92:95], off
	v_mov_b32_dpp v240, v84 row_ror:8 row_mask:0xf bank_mask:0xf
	v_mov_b32_dpp v241, v85 row_ror:8 row_mask:0xf bank_mask:0xf
	v_mov_b32_dpp v242, v86 row_ror:8 row_mask:0xf bank_mask:0xf
	v_mov_b32_dpp v243, v87 row_ror:8 row_mask:0xf bank_mask:0xf
	v_mov_b32_dpp v84, v88 row_ror:8 row_mask:0xf bank_mask:0x3
	v_mov_b32_dpp v85, v89 row_ror:8 row_mask:0xf bank_mask:0x3
; __device__ __forceinline__ void epilogue(const f32x4 (&acc)[2][2][4][2], const Unit& u, LAS unsigned char* lds, int wr, int wc, int fr, int fq) {
;     ...
;             for (int m = 0; m < 4; ++m) { float* rowp = C + (size_t)(row0 + ai * HALF + m * 16) * ldc + col0;
; #pragma unroll
;                 for (int bj = 0; bj < 2; ++bj)
; #pragma unroll
;                     for (int n = 0; n < 2; ++n) { f32x4 v = acc[ai][bj][m][n];
;                         if (mode >= 5) { v += *(const f32x4*)(bias + col0 + bj * HALF + n * 16);
; #pragma unroll
;                             for (int q = 0; q < 4; ++q) { const float sg = __builtin_amdgcn_rcpf(1.f + __expf(-v[q])); v[q] = mode == 5 ? __expf(-0.6065306597126334f * sg) : sg; } }
;                         *(f32x4*)(rowp + bj * HALF + n * 16) = v; }
;                 asm volatile("" ::: "memory"); }
	v_mov_b32_dpp v86, v90 row_ror:8 row_mask:0xf bank_mask:0x3
	v_mov_b32_dpp v87, v91 row_ror:8 row_mask:0xf bank_mask:0x3
	v_mov_b32_dpp v88, v240 quad_perm:[0,1,2,3] row_mask:0xf bank_mask:0xc
	v_mov_b32_dpp v89, v241 quad_perm:[0,1,2,3] row_mask:0xf bank_mask:0xc
	v_mov_b32_dpp v90, v242 quad_perm:[0,1,2,3] row_mask:0xf bank_mask:0xc
	v_mov_b32_dpp v91, v243 quad_perm:[0,1,2,3] row_mask:0xf bank_mask:0xc
	global_store_dwordx4 v[144:145], v[88:91], off offset:512
	global_store_dwordx4 v[142:143], v[84:87], off offset:512
	v_lshl_add_u64 v[144:145], s[2:3], 0, v[144:145]
	v_lshl_add_u64 v[142:143], s[2:3], 0, v[142:143]
	v_mov_b32_dpp v240, v76 row_ror:8 row_mask:0xf bank_mask:0xf
	v_mov_b32_dpp v241, v77 row_ror:8 row_mask:0xf bank_mask:0xf
	v_mov_b32_dpp v242, v78 row_ror:8 row_mask:0xf bank_mask:0xf
	v_mov_b32_dpp v243, v79 row_ror:8 row_mask:0xf bank_mask:0xf
	v_mov_b32_dpp v76, v80 row_ror:8 row_mask:0xf bank_mask:0x3
	v_mov_b32_dpp v77, v81 row_ror:8 row_mask:0xf bank_mask:0x3
	v_mov_b32_dpp v78, v82 row_ror:8 row_mask:0xf bank_mask:0x3
	v_mov_b32_dpp v79, v83 row_ror:8 row_mask:0xf bank_mask:0x3
	v_mov_b32_dpp v80, v240 quad_perm:[0,1,2,3] row_mask:0xf bank_mask:0xc
	v_mov_b32_dpp v81, v241 quad_perm:[0,1,2,3] row_mask:0xf bank_mask:0xc
	v_mov_b32_dpp v82, v242 quad_perm:[0,1,2,3] row_mask:0xf bank_mask:0xc
	v_mov_b32_dpp v83, v243 quad_perm:[0,1,2,3] row_mask:0xf bank_mask:0xc
	global_store_dwordx4 v[144:145], v[80:83], off
	global_store_dwordx4 v[142:143], v[76:79], off
	v_mov_b32_dpp v240, v68 row_ror:8 row_mask:0xf bank_mask:0xf
	v_mov_b32_dpp v241, v69 row_ror:8 row_mask:0xf bank_mask:0xf
	v_mov_b32_dpp v242, v70 row_ror:8 row_mask:0xf bank_mask:0xf
	v_mov_b32_dpp v243, v71 row_ror:8 row_mask:0xf bank_mask:0xf
	v_mov_b32_dpp v68, v72 row_ror:8 row_mask:0xf bank_mask:0x3
	v_mov_b32_dpp v69, v73 row_ror:8 row_mask:0xf bank_mask:0x3
	v_mov_b32_dpp v70, v74 row_ror:8 row_mask:0xf bank_mask:0x3
	v_mov_b32_dpp v71, v75 row_ror:8 row_mask:0xf bank_mask:0x3
	v_mov_b32_dpp v72, v240 quad_perm:[0,1,2,3] row_mask:0xf bank_mask:0xc
	v_mov_b32_dpp v73, v241 quad_perm:[0,1,2,3] row_mask:0xf bank_mask:0xc
	v_mov_b32_dpp v74, v242 quad_perm:[0,1,2,3] row_mask:0xf bank_mask:0xc
	v_mov_b32_dpp v75, v243 quad_perm:[0,1,2,3] row_mask:0xf bank_mask:0xc
	global_store_dwordx4 v[144:145], v[72:75], off offset:512
	global_store_dwordx4 v[142:143], v[68:71], off offset:512
	v_lshl_add_u64 v[144:145], s[2:3], 2, v[144:145]
	v_lshl_add_u64 v[142:143], s[2:3], 2, v[142:143]
	v_lshl_add_u64 v[144:145], s[2:3], 0, v[144:145]
	v_lshl_add_u64 v[142:143], s[2:3], 0, v[142:143]
	v_mov_b32_dpp v240, v60 row_ror:8 row_mask:0xf bank_mask:0xf
	v_mov_b32_dpp v241, v61 row_ror:8 row_mask:0xf bank_mask:0xf
	v_mov_b32_dpp v242, v62 row_ror:8 row_mask:0xf bank_mask:0xf
	v_mov_b32_dpp v243, v63 row_ror:8 row_mask:0xf bank_mask:0xf
	v_mov_b32_dpp v60, v64 row_ror:8 row_mask:0xf bank_mask:0x3
	v_mov_b32_dpp v61, v65 row_ror:8 row_mask:0xf bank_mask:0x3
	v_mov_b32_dpp v62, v66 row_ror:8 row_mask:0xf bank_mask:0x3
	v_mov_b32_dpp v63, v67 row_ror:8 row_mask:0xf bank_mask:0x3
	v_mov_b32_dpp v64, v240 quad_perm:[0,1,2,3] row_mask:0xf bank_mask:0xc
	v_mov_b32_dpp v65, v241 quad_perm:[0,1,2,3] row_mask:0xf bank_mask:0xc
	v_mov_b32_dpp v66, v242 quad_perm:[0,1,2,3] row_mask:0xf bank_mask:0xc
	v_mov_b32_dpp v67, v243 quad_perm:[0,1,2,3] row_mask:0xf bank_mask:0xc
	global_store_dwordx4 v[144:145], v[64:67], off
	global_store_dwordx4 v[142:143], v[60:63], off
	v_mov_b32_dpp v240, v52 row_ror:8 row_mask:0xf bank_mask:0xf
	v_mov_b32_dpp v241, v53 row_ror:8 row_mask:0xf bank_mask:0xf
	v_mov_b32_dpp v242, v54 row_ror:8 row_mask:0xf bank_mask:0xf
	v_mov_b32_dpp v243, v55 row_ror:8 row_mask:0xf bank_mask:0xf
	v_mov_b32_dpp v52, v56 row_ror:8 row_mask:0xf bank_mask:0x3
	v_mov_b32_dpp v53, v57 row_ror:8 row_mask:0xf bank_mask:0x3
	v_mov_b32_dpp v54, v58 row_ror:8 row_mask:0xf bank_mask:0x3
	v_mov_b32_dpp v55, v59 row_ror:8 row_mask:0xf bank_mask:0x3
	v_mov_b32_dpp v56, v240 quad_perm:[0,1,2,3] row_mask:0xf bank_mask:0xc
	v_mov_b32_dpp v57, v241 quad_perm:[0,1,2,3] row_mask:0xf bank_mask:0xc
	v_mov_b32_dpp v58, v242 quad_perm:[0,1,2,3] row_mask:0xf bank_mask:0xc
	v_mov_b32_dpp v59, v243 quad_perm:[0,1,2,3] row_mask:0xf bank_mask:0xc
	global_store_dwordx4 v[144:145], v[56:59], off offset:512
	global_store_dwordx4 v[142:143], v[52:55], off offset:512
	v_lshl_add_u64 v[144:145], s[2:3], 0, v[144:145]
	v_lshl_add_u64 v[142:143], s[2:3], 0, v[142:143]
	v_mov_b32_dpp v240, v44 row_ror:8 row_mask:0xf bank_mask:0xf
	v_mov_b32_dpp v241, v45 row_ror:8 row_mask:0xf bank_mask:0xf
	v_mov_b32_dpp v242, v46 row_ror:8 row_mask:0xf bank_mask:0xf
	v_mov_b32_dpp v243, v47 row_ror:8 row_mask:0xf bank_mask:0xf
	v_mov_b32_dpp v44, v48 row_ror:8 row_mask:0xf bank_mask:0x3
	v_mov_b32_dpp v45, v49 row_ror:8 row_mask:0xf bank_mask:0x3
	v_mov_b32_dpp v46, v50 row_ror:8 row_mask:0xf bank_mask:0x3
	v_mov_b32_dpp v47, v51 row_ror:8 row_mask:0xf bank_mask:0x3
; __device__ __forceinline__ void epilogue(const f32x4 (&acc)[2][2][4][2], const Unit& u, LAS unsigned char* lds, int wr, int wc, int fr, int fq) {
;     ...
;             for (int m = 0; m < 4; ++m) { float* rowp = C + (size_t)(row0 + ai * HALF + m * 16) * ldc + col0;
; #pragma unroll
;                 for (int bj = 0; bj < 2; ++bj)
; #pragma unroll
;                     for (int n = 0; n < 2; ++n) { f32x4 v = acc[ai][bj][m][n];
;                         if (mode >= 5) { v += *(const f32x4*)(bias + col0 + bj * HALF + n * 16);
; #pragma unroll
;                             for (int q = 0; q < 4; ++q) { const float sg = __builtin_amdgcn_rcpf(1.f + __expf(-v[q])); v[q] = mode == 5 ? __expf(-0.6065306597126334f * sg) : sg; } }
;                         *(f32x4*)(rowp + bj * HALF + n * 16) = v; }
;                 asm volatile("" ::: "memory"); }
	v_mov_b32_dpp v48, v240 quad_perm:[0,1,2,3] row_mask:0xf bank_mask:0xc
	v_mov_b32_dpp v49, v241 quad_perm:[0,1,2,3] row_mask:0xf bank_mask:0xc
	v_mov_b32_dpp v50, v242 quad_perm:[0,1,2,3] row_mask:0xf bank_mask:0xc
	v_mov_b32_dpp v51, v243 quad_perm:[0,1,2,3] row_mask:0xf bank_mask:0xc
	global_store_dwordx4 v[144:145], v[48:51], off
	global_store_dwordx4 v[142:143], v[44:47], off
	v_mov_b32_dpp v240, v36 row_ror:8 row_mask:0xf bank_mask:0xf
	v_mov_b32_dpp v241, v37 row_ror:8 row_mask:0xf bank_mask:0xf
	v_mov_b32_dpp v242, v38 row_ror:8 row_mask:0xf bank_mask:0xf
	v_mov_b32_dpp v243, v39 row_ror:8 row_mask:0xf bank_mask:0xf
	v_mov_b32_dpp v36, v40 row_ror:8 row_mask:0xf bank_mask:0x3
	v_mov_b32_dpp v37, v41 row_ror:8 row_mask:0xf bank_mask:0x3
	v_mov_b32_dpp v38, v42 row_ror:8 row_mask:0xf bank_mask:0x3
	v_mov_b32_dpp v39, v43 row_ror:8 row_mask:0xf bank_mask:0x3
	v_mov_b32_dpp v40, v240 quad_perm:[0,1,2,3] row_mask:0xf bank_mask:0xc
	v_mov_b32_dpp v41, v241 quad_perm:[0,1,2,3] row_mask:0xf bank_mask:0xc
	v_mov_b32_dpp v42, v242 quad_perm:[0,1,2,3] row_mask:0xf bank_mask:0xc
	v_mov_b32_dpp v43, v243 quad_perm:[0,1,2,3] row_mask:0xf bank_mask:0xc
	global_store_dwordx4 v[144:145], v[40:43], off offset:512
	global_store_dwordx4 v[142:143], v[36:39], off offset:512
	v_lshl_add_u64 v[144:145], s[2:3], 0, v[144:145]
	v_lshl_add_u64 v[142:143], s[2:3], 0, v[142:143]
	v_mov_b32_dpp v240, v28 row_ror:8 row_mask:0xf bank_mask:0xf
	v_mov_b32_dpp v241, v29 row_ror:8 row_mask:0xf bank_mask:0xf
	v_mov_b32_dpp v242, v30 row_ror:8 row_mask:0xf bank_mask:0xf
	v_mov_b32_dpp v243, v31 row_ror:8 row_mask:0xf bank_mask:0xf
	v_mov_b32_dpp v28, v32 row_ror:8 row_mask:0xf bank_mask:0x3
	v_mov_b32_dpp v29, v33 row_ror:8 row_mask:0xf bank_mask:0x3
	v_mov_b32_dpp v30, v34 row_ror:8 row_mask:0xf bank_mask:0x3
	v_mov_b32_dpp v31, v35 row_ror:8 row_mask:0xf bank_mask:0x3
	v_mov_b32_dpp v32, v240 quad_perm:[0,1,2,3] row_mask:0xf bank_mask:0xc
	v_mov_b32_dpp v33, v241 quad_perm:[0,1,2,3] row_mask:0xf bank_mask:0xc
	v_mov_b32_dpp v34, v242 quad_perm:[0,1,2,3] row_mask:0xf bank_mask:0xc
	v_mov_b32_dpp v35, v243 quad_perm:[0,1,2,3] row_mask:0xf bank_mask:0xc
	global_store_dwordx4 v[144:145], v[32:35], off
	global_store_dwordx4 v[142:143], v[28:31], off
	v_mov_b32_dpp v240, v20 row_ror:8 row_mask:0xf bank_mask:0xf
	v_mov_b32_dpp v241, v21 row_ror:8 row_mask:0xf bank_mask:0xf
	v_mov_b32_dpp v242, v22 row_ror:8 row_mask:0xf bank_mask:0xf
	v_mov_b32_dpp v243, v23 row_ror:8 row_mask:0xf bank_mask:0xf
	v_mov_b32_dpp v20, v24 row_ror:8 row_mask:0xf bank_mask:0x3
	v_mov_b32_dpp v21, v25 row_ror:8 row_mask:0xf bank_mask:0x3
	v_mov_b32_dpp v22, v26 row_ror:8 row_mask:0xf bank_mask:0x3
	v_mov_b32_dpp v23, v27 row_ror:8 row_mask:0xf bank_mask:0x3
	v_mov_b32_dpp v24, v240 quad_perm:[0,1,2,3] row_mask:0xf bank_mask:0xc
	v_mov_b32_dpp v25, v241 quad_perm:[0,1,2,3] row_mask:0xf bank_mask:0xc
	v_mov_b32_dpp v26, v242 quad_perm:[0,1,2,3] row_mask:0xf bank_mask:0xc
	v_mov_b32_dpp v27, v243 quad_perm:[0,1,2,3] row_mask:0xf bank_mask:0xc
	global_store_dwordx4 v[144:145], v[24:27], off offset:512
	global_store_dwordx4 v[142:143], v[20:23], off offset:512
	v_lshl_add_u64 v[144:145], s[2:3], 0, v[144:145]
	v_lshl_add_u64 v[142:143], s[2:3], 0, v[142:143]
	v_mov_b32_dpp v240, v12 row_ror:8 row_mask:0xf bank_mask:0xf
	v_mov_b32_dpp v241, v13 row_ror:8 row_mask:0xf bank_mask:0xf
	v_mov_b32_dpp v242, v14 row_ror:8 row_mask:0xf bank_mask:0xf
	v_mov_b32_dpp v243, v15 row_ror:8 row_mask:0xf bank_mask:0xf
	v_mov_b32_dpp v12, v16 row_ror:8 row_mask:0xf bank_mask:0x3
	v_mov_b32_dpp v13, v17 row_ror:8 row_mask:0xf bank_mask:0x3
	v_mov_b32_dpp v14, v18 row_ror:8 row_mask:0xf bank_mask:0x3
	v_mov_b32_dpp v15, v19 row_ror:8 row_mask:0xf bank_mask:0x3
	v_mov_b32_dpp v16, v240 quad_perm:[0,1,2,3] row_mask:0xf bank_mask:0xc
	v_mov_b32_dpp v17, v241 quad_perm:[0,1,2,3] row_mask:0xf bank_mask:0xc
	v_mov_b32_dpp v18, v242 quad_perm:[0,1,2,3] row_mask:0xf bank_mask:0xc
	v_mov_b32_dpp v19, v243 quad_perm:[0,1,2,3] row_mask:0xf bank_mask:0xc
	global_store_dwordx4 v[144:145], v[16:19], off
	global_store_dwordx4 v[142:143], v[12:15], off
	v_mov_b32_dpp v240, v4 row_ror:8 row_mask:0xf bank_mask:0xf
	v_mov_b32_dpp v241, v5 row_ror:8 row_mask:0xf bank_mask:0xf
	v_mov_b32_dpp v242, v6 row_ror:8 row_mask:0xf bank_mask:0xf
	v_mov_b32_dpp v243, v7 row_ror:8 row_mask:0xf bank_mask:0xf
	v_mov_b32_dpp v4, v8 row_ror:8 row_mask:0xf bank_mask:0x3
	v_mov_b32_dpp v5, v9 row_ror:8 row_mask:0xf bank_mask:0x3
	v_mov_b32_dpp v6, v10 row_ror:8 row_mask:0xf bank_mask:0x3
	v_mov_b32_dpp v7, v11 row_ror:8 row_mask:0xf bank_mask:0x3
	v_mov_b32_dpp v8, v240 quad_perm:[0,1,2,3] row_mask:0xf bank_mask:0xc
	v_mov_b32_dpp v9, v241 quad_perm:[0,1,2,3] row_mask:0xf bank_mask:0xc
	v_mov_b32_dpp v10, v242 quad_perm:[0,1,2,3] row_mask:0xf bank_mask:0xc
	v_mov_b32_dpp v11, v243 quad_perm:[0,1,2,3] row_mask:0xf bank_mask:0xc
	global_store_dwordx4 v[144:145], v[8:11], off offset:512
	global_store_dwordx4 v[142:143], v[4:7], off offset:512
	s_branch .LBB0_1310
